# rms/final-norm phases: the 512 sample rows spread over all workgroups (waves 3 and 7 of each) instead of the last 64 workgroups
# speedup vs baseline: 1.0056x; 1.0045x over previous
.LBB0_562:
	v_readlane_b32 s0, v251, 19
	s_not_b32 s0, s0
	s_add_i32 s2, s56, s0
	s_and_b32 s98, s2, 3
	s_lshr_b32 s2, s2, 2
	s_cmp_eq_u32 s98, 0
	s_cselect_b32 s2, s2, 0x4000
	s_mov_b32 s0, s2
	v_writelane_b32 v251, s0, 33
	s_cmpk_lt_i32 s2, 0x200
	s_nop 0
	v_writelane_b32 v251, s1, 34
	s_cselect_b64 s[0:1], -1, 0
	v_writelane_b32 v251, s0, 35
	s_and_b64 vcc, exec, s[0:1]
	s_nop 0
	v_writelane_b32 v251, s1, 36
	s_cbranch_vccz .LBB0_565
	v_mbcnt_hi_u32_b32 v0, -1, v250
	v_and_b32_e32 v1, 64, v0
	v_add_u32_e32 v1, 64, v1
	v_xor_b32_e32 v2, 1, v0
	v_cmp_lt_i32_e32 vcc, v2, v1
	v_readlane_b32 s0, v252, 16
	v_readlane_b32 s1, v252, 17
	v_cndmask_b32_e32 v2, v0, v2, vcc
	v_lshlrev_b32_e32 v24, 2, v2
	v_xor_b32_e32 v2, 2, v0
	v_cmp_lt_i32_e32 vcc, v2, v1
	v_readlane_b32 s8, v252, 24
	v_readlane_b32 s9, v252, 25
	v_cndmask_b32_e32 v2, v0, v2, vcc
	v_lshlrev_b32_e32 v25, 2, v2
	v_xor_b32_e32 v2, 4, v0
	v_cmp_lt_i32_e32 vcc, v2, v1
	v_readlane_b32 s0, v251, 33
	v_lshlrev_b64 v[18:19], 4, v[64:65]
	v_cndmask_b32_e32 v2, v0, v2, vcc
	v_lshlrev_b32_e32 v26, 2, v2
	v_xor_b32_e32 v2, 8, v0
	v_cmp_lt_i32_e32 vcc, v2, v1
	v_readlane_b32 s4, v252, 20
	v_readlane_b32 s5, v252, 21
	v_cndmask_b32_e32 v2, v0, v2, vcc
	v_lshlrev_b32_e32 v27, 2, v2
	v_xor_b32_e32 v2, 16, v0
	s_mov_b32 s8, s0
	s_ashr_i32 s9, s0, 31
	v_cmp_lt_i32_e32 vcc, v2, v1
	v_lshl_add_u64 v[20:21], s[4:5], 0, v[18:19]
	s_lshl_b64 s[4:5], s[8:9], 12
	v_cndmask_b32_e32 v2, v0, v2, vcc
	v_readlane_b32 s1, v251, 34
	s_add_u32 s0, s48, s4
	v_lshlrev_b32_e32 v28, 2, v2
	v_xor_b32_e32 v2, 32, v0
	v_readlane_b32 s2, v252, 18
	v_readlane_b32 s3, v252, 19
	v_readlane_b32 s6, v252, 22
	s_addc_u32 s1, s49, s5
	s_ashr_i32 s57, s56, 31
	v_cmp_lt_i32_e32 vcc, v2, v1
	v_readlane_b32 s7, v252, 23
	s_lshl_b64 s[2:3], s[56:57], 12
	s_mov_b32 s6, s8
	v_cndmask_b32_e32 v0, v0, v2, vcc
	s_add_u32 s4, s50, s4
	v_writelane_b32 v251, s6, 33
	v_lshlrev_b32_e32 v29, 2, v0
	v_lshl_add_u64 v[16:17], v[64:65], 3, s[60:61]
	s_addc_u32 s5, s51, s5
	v_mov_b32_e32 v30, 0x358637bd
	v_writelane_b32 v251, s7, 34
	v_readlane_b32 s10, v252, 26
	v_readlane_b32 s11, v252, 27
	v_readlane_b32 s12, v252, 28
	v_readlane_b32 s13, v252, 29
	v_readlane_b32 s14, v252, 30
	v_readlane_b32 s15, v252, 31
